# v8 + P5 epilogue loads hoisted + static priority raise for waves 4-7 during FoX
# speedup vs baseline: 1.0216x; 1.0079x over previous
; DI int get_tid() { int t = threadIdx.x; asm volatile("" : "+v"(t)); return t; }
; __global__ void __launch_bounds__(512, 2) fwd_megakernel(Params p) {
;     ...
;     { const int tl = get_tid() & 63; float gq = fabsf(p.fox_q_g[tl]), gk = fabsf(p.fox_k_g[tl]);
; #pragma unroll
;       for (int o = 1; o < 64; o <<= 1) { gq = fmaxf(gq, __shfl_xor(gq, o)); gk = fmaxf(gk, __shfl_xor(gk, o)); }
;       const float bqk = 64.0f * gq * gk * 0.125f * LOG2E * 1.02f, thr2 = 150.0f + bqk;
;       if (G == 256) { const int bh = (bx & 7) * 4 + (bx >> 6), j = (bx >> 3) & 7;
;           fox_bh_setup(bh, p, lds);
;           for (int i = 3; i >= 0; --i) fox_unit(bh, j + 8 * i, p, lds, thr2); }
;       else { for (int u = bx; u < 1024; u += G) { fox_bh_setup(u >> 5, p, lds); fox_unit(u >> 5, u & 31, p, lds, thr2); } } }
.LBB0_436:
	v_mov_b32_e32 v0, v208
	s_waitcnt vmcnt(0)
	s_barrier
	v_readfirstlane_b32 s100, v208
	s_lshr_b32 s100, s100, 8
	s_cmp_lg_u32 s100, 0
	s_cbranch_scc0 .Lfox_prio_done
	s_setprio 1
.Lfox_prio_done:
	v_and_b32_e32 v211, 64, v206
	v_and_b32_e32 v0, 63, v0
	v_lshlrev_b32_e32 v0, 2, v0
	global_load_dword v1, v0, s[26:27]
	s_nop 0
	global_load_dword v0, v0, s[28:29]
	v_xor_b32_e32 v2, 1, v206
	v_add_u32_e32 v8, 64, v211
	v_cmp_lt_i32_e32 vcc, v2, v8
	v_xor_b32_e32 v3, 2, v206
	v_xor_b32_e32 v4, 4, v206
	v_cndmask_b32_e32 v2, v206, v2, vcc
	v_lshlrev_b32_e32 v2, 2, v2
	v_cmp_lt_i32_e32 vcc, v3, v8
	v_xor_b32_e32 v5, 8, v206
	v_xor_b32_e32 v6, 16, v206
	v_cndmask_b32_e32 v3, v206, v3, vcc
	v_lshlrev_b32_e32 v3, 2, v3
	v_cmp_lt_i32_e32 vcc, v4, v8
	v_xor_b32_e32 v7, 32, v206
	v_readlane_b32 s0, v254, 37
	v_cndmask_b32_e32 v4, v206, v4, vcc
	v_lshlrev_b32_e32 v4, 2, v4
	v_cmp_lt_i32_e32 vcc, v5, v8
	s_add_u32 s83, s76, 0x16000000
	v_mov_b32_e32 v207, 0x43160000
	v_readlane_b32 s1, v254, 38
	s_addc_u32 s88, s77, 0
	s_mov_b64 s[20:21], -1
	s_waitcnt vmcnt(1)
	v_and_b32_e32 v9, 0x7fffffff, v1
	s_waitcnt vmcnt(0)
	v_and_b32_e32 v10, 0x7fffffff, v0
	ds_bpermute_b32 v9, v2, v9
	ds_bpermute_b32 v2, v2, v10
	v_max_f32_e64 v1, |v1|, |v1|
	v_max_f32_e64 v0, |v0|, |v0|
	s_waitcnt lgkmcnt(1)
	v_max_f32_e32 v9, v9, v9
	s_waitcnt lgkmcnt(0)
	v_max_f32_e32 v2, v2, v2
	v_max_f32_e32 v1, v1, v9
	v_max_f32_e32 v0, v0, v2
	ds_bpermute_b32 v2, v3, v1
	ds_bpermute_b32 v3, v3, v0
	s_waitcnt lgkmcnt(1)
	v_max_f32_e32 v2, v2, v2
	s_waitcnt lgkmcnt(0)
	v_max_f32_e32 v3, v3, v3
	v_max_f32_e32 v1, v1, v2
	v_max_f32_e32 v0, v0, v3
	ds_bpermute_b32 v2, v4, v1
	ds_bpermute_b32 v3, v4, v0
	v_cndmask_b32_e32 v4, v206, v5, vcc
	v_lshlrev_b32_e32 v4, 2, v4
	v_cmp_lt_i32_e32 vcc, v6, v8
	s_waitcnt lgkmcnt(1)
	v_max_f32_e32 v2, v2, v2
	s_waitcnt lgkmcnt(0)
	v_max_f32_e32 v3, v3, v3
	v_max_f32_e32 v1, v1, v2
	v_max_f32_e32 v0, v0, v3
	ds_bpermute_b32 v2, v4, v1
	ds_bpermute_b32 v3, v4, v0
	v_cndmask_b32_e32 v4, v206, v6, vcc
	v_lshlrev_b32_e32 v209, 2, v4
	v_cmp_lt_i32_e32 vcc, v7, v8
	s_waitcnt lgkmcnt(1)
	v_max_f32_e32 v2, v2, v2
	s_waitcnt lgkmcnt(0)
	v_max_f32_e32 v3, v3, v3
	v_max_f32_e32 v1, v1, v2
	v_max_f32_e32 v0, v0, v3
	ds_bpermute_b32 v2, v209, v1
	ds_bpermute_b32 v3, v209, v0
	v_cndmask_b32_e32 v4, v206, v7, vcc
	v_lshlrev_b32_e32 v210, 2, v4
	s_andn2_b64 vcc, exec, s[0:1]
	s_waitcnt lgkmcnt(1)
	v_max_f32_e32 v2, v2, v2
	s_waitcnt lgkmcnt(0)
	v_max_f32_e32 v3, v3, v3
	v_max_f32_e32 v1, v1, v2
	v_max_f32_e32 v0, v0, v3
	ds_bpermute_b32 v2, v210, v1
	ds_bpermute_b32 v3, v210, v0
	s_waitcnt lgkmcnt(1)
	v_max_f32_e32 v2, v2, v2
	s_waitcnt lgkmcnt(0)
	v_max_f32_e32 v3, v3, v3
	v_max_f32_e32 v1, v1, v2
	v_max_f32_e32 v0, v0, v3
	v_mul_f32_e32 v1, 0x42800000, v1
	v_mul_f32_e32 v0, v0, v1
	v_mul_f32_e32 v0, 0x3e000000, v0
	v_mul_f32_e32 v0, 0x3fb8aa3b, v0
	v_fmac_f32_e32 v207, 0x3f828f5c, v0
	s_cbranch_vccnz .LBB0_502
	s_cmpk_gt_i32 s2, 0x3ff
	s_cbranch_scc1 .LBB0_501
	v_add_u32_e32 v0, -1, v206
	v_cmp_lt_i32_e32 vcc, v0, v211
	s_lshl_b32 s0, s92, 8
	v_mov_b32_e32 v1, 0
	v_cndmask_b32_e32 v0, v0, v206, vcc
	v_lshlrev_b32_e32 v212, 2, v0
	v_add_u32_e32 v0, -2, v206
	v_cmp_lt_i32_e32 vcc, v0, v211
	s_mov_b32 s27, 0
	s_movk_i32 s1, 0x1a00
	v_cndmask_b32_e32 v0, v0, v206, vcc
	v_lshlrev_b32_e32 v213, 2, v0
	v_add_u32_e32 v0, -4, v206
	v_cmp_lt_i32_e32 vcc, v0, v211
	v_mov_b64_e32 v[166:167], s[14:15]
	v_mov_b32_e32 v218, 0x1a00
	v_cndmask_b32_e32 v0, v0, v206, vcc
	v_lshlrev_b32_e32 v214, 2, v0
	v_add_u32_e32 v0, -8, v206
	v_cmp_lt_i32_e32 vcc, v0, v211
	s_add_i32 s4, 0, 0x12a00
	s_add_i32 s5, 0, 0x12400
	v_cndmask_b32_e32 v0, v0, v206, vcc
	v_lshlrev_b32_e32 v215, 2, v0
	v_add_u32_e32 v0, -16, v206
	v_cmp_lt_i32_e32 vcc, v0, v211
	s_add_i32 s6, 0, 0x12000
	s_mov_b32 s7, 0xff800000
	v_cndmask_b32_e32 v0, v0, v206, vcc
	v_lshlrev_b32_e32 v216, 2, v0
	v_subrev_u32_e32 v0, 32, v206
	v_cmp_lt_i32_e32 vcc, v0, v211
	v_mov_b32_e32 v219, 0xff800000
	s_mov_b32 s12, s2
	v_cndmask_b32_e32 v0, v0, v206, vcc
	v_lshlrev_b32_e32 v217, 2, v0
	s_branch .LBB0_440

; #define GSYNC() xcd_barrier(xbar)
; DI void xcd_barrier(const XcdBarrier& b) {
;     asm volatile("s_waitcnt vmcnt(0)" ::: "memory");
;     __syncthreads();
;     if (threadIdx.x == 0) {
;         unsigned* bar = b.bar;
;         __builtin_amdgcn_s_waitcnt(0);
;         unsigned nloc = b.st[0], nx = b.st[1];
;         if (nloc == 0u) { xcd_barrier_complete(bar, b.x, nloc, nx); b.st[0] = nloc; b.st[1] = nx; }
; __global__ void __launch_bounds__(512, 2) fwd_megakernel(Params p) {
;     ...
;     GSYNC();
.LBB0_566:
	s_setprio 0
	s_waitcnt vmcnt(0)
	s_barrier
	s_mov_b64 s[0:1], exec
	v_readlane_b32 s4, v254, 16
	v_readlane_b32 s5, v254, 17
	s_and_b64 s[4:5], s[0:1], s[4:5]
	s_xor_b64 s[20:21], s[4:5], s[0:1]
	s_mov_b64 exec, s[4:5]
	s_cbranch_execz .LBB0_615
	s_add_i32 s0, 0, 0x22000
	v_mov_b32_e32 v0, s0
	s_waitcnt vmcnt(0) expcnt(0) lgkmcnt(0)
	ds_read_b32 v2, v0
	s_add_i32 s0, 0, 0x22004
	v_mov_b32_e32 v0, s0
	ds_read_b32 v0, v0
	s_waitcnt lgkmcnt(1)
	v_cmp_ne_u32_e32 vcc, 0, v2
	s_cbranch_vccnz .LBB0_582
	s_mov_b32 s0, 1
	v_mov_b32_e32 v16, 0
	s_branch .LBB0_570

; #define PG8_STAGE(bufoff, gbase, voff) do { _Pragma("unroll") for (int _i = 0; _i < 2; ++_i) \
;         __builtin_amdgcn_global_load_lds((const unsigned*)((const char*)(gbase) + (voff)[_i]), (LAS unsigned*)(lds + (bufoff) + ldsw + _i * 8192), 16, 0, 0); } while (0)
; #define PG8_LDA(dst, b, h) do { _Pragma("unroll") for (int m = 0; m < 4; ++m) _Pragma("unroll") for (int k = 0; k < 2; ++k) dst[m][k] = *(const LAS bf16x8*)(lds + PG8_SA(b, h) + aoff + m * 2048 + k * 1024); } while (0)
; #define PG8_LDB(dst, b, h) do { _Pragma("unroll") for (int n = 0; n < 2; ++n) _Pragma("unroll") for (int k = 0; k < 2; ++k) dst[n][k] = *(const LAS bf16x8*)(lds + PG8_SB(b, h) + boff + n * 2048 + k * 1024); } while (0)
; #define PG8_MMA(ai, bj, At, Bt) do { __builtin_amdgcn_s_setprio(1); _Pragma("unroll") for (int m = 0; m < 4; ++m) _Pragma("unroll") for (int n = 0; n < 2; ++n) _Pragma("unroll") for (int k = 0; k < 2; ++k) \
;         acc[ai][bj][m][n] = __builtin_amdgcn_mfma_f32_16x16x32_bf16(Bt[n][k], At[m][k], acc[ai][bj][m][n], 0, 0, 0); __builtin_amdgcn_s_setprio(0); } while (0)
; #define PG8_WAIT_V(n) asm volatile("s_waitcnt vmcnt(" #n ")" ::: "memory")
; #define PG8_WAIT_L(n) asm volatile("s_waitcnt lgkmcnt(" #n ")" ::: "memory")
; #define PG8_BAR __builtin_amdgcn_s_barrier()
; #define PG8_SCHED __builtin_amdgcn_sched_barrier(0)
; template <class GEO, class Epi>
; __device__ __forceinline__ void gemm_phase(LAS unsigned char* lds, const Gemm g, const StaticOrder& S, const Epi& E) {
;     ...
;             PG8_LDB(B0, 0, 0); PG8_LDB(B1, 0, 1); PG8_SCHED; PG8_LDA(At, 0, 0); PG8_STAGE(PG8_SA(1, 1), a1 + hstepA, voffA);
;             PG8_WAIT_V(8); PG8_WAIT_L(0); PG8_BAR; PG8_MMA(0, 0, At, B0); PG8_MMA(0, 1, At, B1); PG8_BAR; PG8_SCHED;
;             PG8_LDA(At, 0, 1); PG8_STAGE(PG8_SB(0, 0), b2, voffB); PG8_STAGE(PG8_SB(0, 1), b2 + hstepB, voffB); PG8_STAGE(PG8_SA(0, 0), a2, voffA);
;             PG8_WAIT_V(8); PG8_WAIT_L(0); PG8_BAR; PG8_MMA(1, 0, At, B0); PG8_MMA(1, 1, At, B1); PG8_BAR; PG8_SCHED;
.LBB0_779:
	ds_read_b128 v[148:151], v179
	ds_read_b128 v[152:155], v179 offset:1024
	ds_read_b128 v[156:159], v179 offset:2048
	ds_read_b128 v[166:169], v179 offset:3072
	ds_read_b128 v[186:189], v181
	ds_read_b128 v[190:193], v181 offset:1024
	ds_read_b128 v[194:197], v181 offset:2048
	ds_read_b128 v[198:201], v181 offset:3072
	s_add_u32 s8, s52, 0xfffc0080
	s_addc_u32 s9, s53, -1
	s_cmp_eq_u32 s69, 12
	s_cselect_b32 s57, s45, s9
	s_cselect_b32 s56, s47, s8
	s_cselect_b32 s55, s16, s68
	s_cselect_b32 s54, s66, s67
	v_lshl_add_u64 v[160:161], s[52:53], 0, v[140:141]
	s_add_i32 m0, s1, 0xc000
	ds_read_b128 v[202:205], v183
	ds_read_b128 v[212:215], v183 offset:1024
	ds_read_b128 v[216:219], v183 offset:2048
	ds_read_b128 v[220:223], v183 offset:3072
	ds_read_b128 v[224:227], v183 offset:4096
	ds_read_b128 v[228:231], v183 offset:5120
	ds_read_b128 v[232:235], v183 offset:6144
	ds_read_b128 v[236:239], v183 offset:7168
	global_load_lds_dwordx4 v[160:161], off
	v_lshl_add_u64 v[160:161], s[52:53], 0, v[142:143]
	s_add_i32 m0, s1, 0xe000
	s_nop 0
	global_load_lds_dwordx4 v[160:161], off
	s_waitcnt vmcnt(8)
	s_waitcnt lgkmcnt(0)
	s_barrier
	s_setprio 1
	s_waitcnt lgkmcnt(0)
	v_mfma_f32_16x16x32_bf16 v[124:127], v[148:151], v[202:205], v[124:127]
	v_mfma_f32_16x16x32_bf16 v[120:123], v[156:159], v[202:205], v[120:123]
	v_mfma_f32_16x16x32_bf16 v[112:115], v[148:151], v[216:219], v[112:115]
	v_mfma_f32_16x16x32_bf16 v[104:107], v[156:159], v[216:219], v[104:107]
	v_mfma_f32_16x16x32_bf16 v[96:99], v[148:151], v[224:227], v[96:99]
	v_mfma_f32_16x16x32_bf16 v[88:91], v[156:159], v[224:227], v[88:91]
	v_mfma_f32_16x16x32_bf16 v[80:83], v[148:151], v[232:235], v[80:83]
	v_mfma_f32_16x16x32_bf16 v[72:75], v[156:159], v[232:235], v[72:75]
	v_mfma_f32_16x16x32_bf16 v[124:127], v[152:155], v[212:215], v[124:127]
	v_mfma_f32_16x16x32_bf16 v[120:123], v[166:169], v[212:215], v[120:123]
	v_mfma_f32_16x16x32_bf16 v[112:115], v[152:155], v[220:223], v[112:115]
	v_mfma_f32_16x16x32_bf16 v[104:107], v[166:169], v[220:223], v[104:107]
	v_mfma_f32_16x16x32_bf16 v[96:99], v[152:155], v[228:231], v[96:99]
	v_mfma_f32_16x16x32_bf16 v[88:91], v[166:169], v[228:231], v[88:91]
	v_mfma_f32_16x16x32_bf16 v[80:83], v[152:155], v[236:239], v[80:83]
	v_mfma_f32_16x16x32_bf16 v[72:75], v[166:169], v[236:239], v[72:75]
	s_setprio 0
	s_setprio 1
	v_mfma_f32_16x16x32_bf16 v[116:119], v[186:189], v[202:205], v[116:119]
	v_mfma_f32_16x16x32_bf16 v[108:111], v[194:197], v[202:205], v[108:111]
	v_mfma_f32_16x16x32_bf16 v[100:103], v[186:189], v[216:219], v[100:103]
	v_mfma_f32_16x16x32_bf16 v[92:95], v[194:197], v[216:219], v[92:95]
	v_mfma_f32_16x16x32_bf16 v[84:87], v[186:189], v[224:227], v[84:87]
	v_mfma_f32_16x16x32_bf16 v[76:79], v[194:197], v[224:227], v[76:79]
	v_mfma_f32_16x16x32_bf16 v[68:71], v[186:189], v[232:235], v[68:71]
	v_mfma_f32_16x16x32_bf16 v[64:67], v[194:197], v[232:235], v[64:67]
	v_mfma_f32_16x16x32_bf16 v[116:119], v[190:193], v[212:215], v[116:119]
	v_mfma_f32_16x16x32_bf16 v[108:111], v[198:201], v[212:215], v[108:111]
	v_mfma_f32_16x16x32_bf16 v[100:103], v[190:193], v[220:223], v[100:103]
	v_mfma_f32_16x16x32_bf16 v[92:95], v[198:201], v[220:223], v[92:95]
	v_mfma_f32_16x16x32_bf16 v[84:87], v[190:193], v[228:231], v[84:87]
	v_mfma_f32_16x16x32_bf16 v[76:79], v[198:201], v[228:231], v[76:79]
	v_mfma_f32_16x16x32_bf16 v[68:71], v[190:193], v[236:239], v[68:71]
	v_mfma_f32_16x16x32_bf16 v[64:67], v[198:201], v[236:239], v[64:67]
	s_setprio 0
	s_barrier
	s_add_i32 s8, s60, s0
	v_lshl_add_u64 v[160:161], s[54:55], 0, v[130:131]
	s_mov_b32 m0, s8
	ds_read_b128 v[202:205], v183 offset:16384
	ds_read_b128 v[212:215], v183 offset:17408
	ds_read_b128 v[216:219], v183 offset:18432
	ds_read_b128 v[220:223], v183 offset:19456
	ds_read_b128 v[224:227], v183 offset:20480
	ds_read_b128 v[228:231], v183 offset:21504
	ds_read_b128 v[232:235], v183 offset:22528
	ds_read_b128 v[236:239], v183 offset:23552
	global_load_lds_dwordx4 v[160:161], off
	s_add_i32 m0, s8, 0x2000
	s_add_u32 s8, s54, 0x40000
	v_lshl_add_u64 v[170:171], s[54:55], 0, v[134:135]
	s_addc_u32 s9, s55, 0
	s_add_i32 s38, s61, s0
	global_load_lds_dwordx4 v[170:171], off
	v_lshl_add_u64 v[206:207], s[8:9], 0, v[130:131]
	s_mov_b32 m0, s38
	v_lshl_add_u64 v[240:241], s[56:57], 0, v[132:133]
	global_load_lds_dwordx4 v[206:207], off
	v_lshl_add_u64 v[206:207], s[8:9], 0, v[134:135]
	s_add_i32 m0, s38, 0x2000
	s_nop 0
	global_load_lds_dwordx4 v[206:207], off
	v_lshl_add_u64 v[206:207], s[56:57], 0, v[128:129]
	s_mov_b32 m0, s1
	s_nop 0
	global_load_lds_dwordx4 v[206:207], off
	s_mov_b32 m0, s4
	s_nop 0
	global_load_lds_dwordx4 v[240:241], off
	s_waitcnt vmcnt(8)
	s_waitcnt lgkmcnt(0)
	s_barrier
; #define PG8_STAGE(bufoff, gbase, voff) do { _Pragma("unroll") for (int _i = 0; _i < 2; ++_i) \
;         __builtin_amdgcn_global_load_lds((const unsigned*)((const char*)(gbase) + (voff)[_i]), (LAS unsigned*)(lds + (bufoff) + ldsw + _i * 8192), 16, 0, 0); } while (0)
; #define PG8_LDA(dst, b, h) do { _Pragma("unroll") for (int m = 0; m < 4; ++m) _Pragma("unroll") for (int k = 0; k < 2; ++k) dst[m][k] = *(const LAS bf16x8*)(lds + PG8_SA(b, h) + aoff + m * 2048 + k * 1024); } while (0)
; #define PG8_LDB(dst, b, h) do { _Pragma("unroll") for (int n = 0; n < 2; ++n) _Pragma("unroll") for (int k = 0; k < 2; ++k) dst[n][k] = *(const LAS bf16x8*)(lds + PG8_SB(b, h) + boff + n * 2048 + k * 1024); } while (0)
; #define PG8_MMA(ai, bj, At, Bt) do { __builtin_amdgcn_s_setprio(1); _Pragma("unroll") for (int m = 0; m < 4; ++m) _Pragma("unroll") for (int n = 0; n < 2; ++n) _Pragma("unroll") for (int k = 0; k < 2; ++k) \
;         acc[ai][bj][m][n] = __builtin_amdgcn_mfma_f32_16x16x32_bf16(Bt[n][k], At[m][k], acc[ai][bj][m][n], 0, 0, 0); __builtin_amdgcn_s_setprio(0); } while (0)
; #define PG8_WAIT_V(n) asm volatile("s_waitcnt vmcnt(" #n ")" ::: "memory")
; #define PG8_WAIT_L(n) asm volatile("s_waitcnt lgkmcnt(" #n ")" ::: "memory")
; #define PG8_BAR __builtin_amdgcn_s_barrier()
; #define PG8_SCHED __builtin_amdgcn_sched_barrier(0)
; template <class GEO, class Epi>
; __device__ __forceinline__ void gemm_phase(LAS unsigned char* lds, const Gemm g, const StaticOrder& S, const Epi& E) {
;     ...
;             PG8_WAIT_V(8); PG8_WAIT_L(0); PG8_BAR; PG8_MMA(1, 0, At, B0); PG8_MMA(1, 1, At, B1); PG8_BAR; PG8_SCHED;
;             PG8_LDB(B0, 1, 0); PG8_LDB(B1, 1, 1); PG8_SCHED; PG8_LDA(At, 1, 0); PG8_STAGE(PG8_SA(0, 1), a2 + hstepA, voffA);
;             PG8_WAIT_V(8); PG8_WAIT_L(0); PG8_BAR; PG8_MMA(0, 0, At, B0); PG8_MMA(0, 1, At, B1); PG8_BAR; PG8_SCHED;
	s_setprio 1
	s_waitcnt lgkmcnt(0)
	v_mfma_f32_16x16x32_bf16 v[60:63], v[148:151], v[202:205], v[60:63]
	v_mfma_f32_16x16x32_bf16 v[56:59], v[156:159], v[202:205], v[56:59]
	v_mfma_f32_16x16x32_bf16 v[48:51], v[148:151], v[216:219], v[48:51]
	v_mfma_f32_16x16x32_bf16 v[40:43], v[156:159], v[216:219], v[40:43]
	v_mfma_f32_16x16x32_bf16 v[32:35], v[148:151], v[224:227], v[32:35]
	v_mfma_f32_16x16x32_bf16 v[24:27], v[156:159], v[224:227], v[24:27]
	v_mfma_f32_16x16x32_bf16 v[16:19], v[148:151], v[232:235], v[16:19]
	v_mfma_f32_16x16x32_bf16 v[8:11], v[156:159], v[232:235], v[8:11]
	v_mfma_f32_16x16x32_bf16 v[60:63], v[152:155], v[212:215], v[60:63]
	v_mfma_f32_16x16x32_bf16 v[56:59], v[166:169], v[212:215], v[56:59]
	v_mfma_f32_16x16x32_bf16 v[48:51], v[152:155], v[220:223], v[48:51]
	v_mfma_f32_16x16x32_bf16 v[40:43], v[166:169], v[220:223], v[40:43]
	v_mfma_f32_16x16x32_bf16 v[32:35], v[152:155], v[228:231], v[32:35]
	v_mfma_f32_16x16x32_bf16 v[24:27], v[166:169], v[228:231], v[24:27]
	v_mfma_f32_16x16x32_bf16 v[16:19], v[152:155], v[236:239], v[16:19]
	v_mfma_f32_16x16x32_bf16 v[8:11], v[166:169], v[236:239], v[8:11]
	s_setprio 0
	s_setprio 1
	v_mfma_f32_16x16x32_bf16 v[52:55], v[186:189], v[202:205], v[52:55]
	v_mfma_f32_16x16x32_bf16 v[44:47], v[194:197], v[202:205], v[44:47]
	v_mfma_f32_16x16x32_bf16 v[36:39], v[186:189], v[216:219], v[36:39]
	v_mfma_f32_16x16x32_bf16 v[28:31], v[194:197], v[216:219], v[28:31]
	v_mfma_f32_16x16x32_bf16 v[20:23], v[186:189], v[224:227], v[20:23]
	v_mfma_f32_16x16x32_bf16 v[12:15], v[194:197], v[224:227], v[12:15]
	v_mfma_f32_16x16x32_bf16 v[4:7], v[186:189], v[232:235], v[4:7]
	v_mfma_f32_16x16x32_bf16 v[0:3], v[194:197], v[232:235], v[0:3]
	v_mfma_f32_16x16x32_bf16 v[52:55], v[190:193], v[212:215], v[52:55]
	v_mfma_f32_16x16x32_bf16 v[44:47], v[198:201], v[212:215], v[44:47]
	v_mfma_f32_16x16x32_bf16 v[36:39], v[190:193], v[220:223], v[36:39]
	v_mfma_f32_16x16x32_bf16 v[28:31], v[198:201], v[220:223], v[28:31]
	v_mfma_f32_16x16x32_bf16 v[20:23], v[190:193], v[228:231], v[20:23]
	v_mfma_f32_16x16x32_bf16 v[12:15], v[198:201], v[228:231], v[12:15]
	v_mfma_f32_16x16x32_bf16 v[4:7], v[190:193], v[236:239], v[4:7]
	v_mfma_f32_16x16x32_bf16 v[0:3], v[198:201], v[236:239], v[0:3]
	s_setprio 0
	s_barrier
	s_add_i32 s38, 0, 0x18000
	s_add_i32 s39, 0, 0x1c000
	v_add_u32_e32 v166, s38, v175
	v_add_u32_e32 v172, s39, v175
	ds_read_b128 v[148:151], v166
	ds_read_b128 v[152:155], v166 offset:1024
	ds_read_b128 v[156:159], v166 offset:2048
	ds_read_b128 v[166:169], v166 offset:3072
	ds_read_b128 v[186:189], v172
	ds_read_b128 v[190:193], v172 offset:1024
	ds_read_b128 v[194:197], v172 offset:2048
	ds_read_b128 v[198:201], v172 offset:3072
	s_add_u32 s8, s56, 0x40000
	s_addc_u32 s9, s57, 0
	s_mov_b32 m0, s5
	v_lshl_add_u64 v[242:243], s[8:9], 0, v[128:129]
	ds_read_b128 v[202:205], v183 offset:32768
	ds_read_b128 v[212:215], v183 offset:33792
	ds_read_b128 v[216:219], v183 offset:34816
	ds_read_b128 v[220:223], v183 offset:35840
	ds_read_b128 v[224:227], v183 offset:36864
	ds_read_b128 v[228:231], v183 offset:37888
	ds_read_b128 v[232:235], v183 offset:38912
	ds_read_b128 v[236:239], v183 offset:39936
	global_load_lds_dwordx4 v[242:243], off
	v_lshl_add_u64 v[242:243], s[8:9], 0, v[132:133]
	s_mov_b32 m0, s6
	s_nop 0
	global_load_lds_dwordx4 v[242:243], off
	s_waitcnt vmcnt(8)
	s_waitcnt lgkmcnt(0)
	s_barrier
	s_setprio 1
	s_waitcnt lgkmcnt(0)
	v_mfma_f32_16x16x32_bf16 v[124:127], v[148:151], v[202:205], v[124:127]
	v_mfma_f32_16x16x32_bf16 v[120:123], v[156:159], v[202:205], v[120:123]
	v_mfma_f32_16x16x32_bf16 v[112:115], v[148:151], v[216:219], v[112:115]
	v_mfma_f32_16x16x32_bf16 v[104:107], v[156:159], v[216:219], v[104:107]
	v_mfma_f32_16x16x32_bf16 v[96:99], v[148:151], v[224:227], v[96:99]
	v_mfma_f32_16x16x32_bf16 v[88:91], v[156:159], v[224:227], v[88:91]
	v_mfma_f32_16x16x32_bf16 v[80:83], v[148:151], v[232:235], v[80:83]
	v_mfma_f32_16x16x32_bf16 v[72:75], v[156:159], v[232:235], v[72:75]
	v_mfma_f32_16x16x32_bf16 v[124:127], v[152:155], v[212:215], v[124:127]
	v_mfma_f32_16x16x32_bf16 v[120:123], v[166:169], v[212:215], v[120:123]
	v_mfma_f32_16x16x32_bf16 v[112:115], v[152:155], v[220:223], v[112:115]
	v_mfma_f32_16x16x32_bf16 v[104:107], v[166:169], v[220:223], v[104:107]
	v_mfma_f32_16x16x32_bf16 v[96:99], v[152:155], v[228:231], v[96:99]
	v_mfma_f32_16x16x32_bf16 v[88:91], v[166:169], v[228:231], v[88:91]
	v_mfma_f32_16x16x32_bf16 v[80:83], v[152:155], v[236:239], v[80:83]
	v_mfma_f32_16x16x32_bf16 v[72:75], v[166:169], v[236:239], v[72:75]
	s_setprio 0
	s_setprio 1
	v_mfma_f32_16x16x32_bf16 v[116:119], v[186:189], v[202:205], v[116:119]
	v_mfma_f32_16x16x32_bf16 v[108:111], v[194:197], v[202:205], v[108:111]
	v_mfma_f32_16x16x32_bf16 v[100:103], v[186:189], v[216:219], v[100:103]
	v_mfma_f32_16x16x32_bf16 v[92:95], v[194:197], v[216:219], v[92:95]
	v_mfma_f32_16x16x32_bf16 v[84:87], v[186:189], v[224:227], v[84:87]
	v_mfma_f32_16x16x32_bf16 v[76:79], v[194:197], v[224:227], v[76:79]
	v_mfma_f32_16x16x32_bf16 v[68:71], v[186:189], v[232:235], v[68:71]
	v_mfma_f32_16x16x32_bf16 v[64:67], v[194:197], v[232:235], v[64:67]
	v_mfma_f32_16x16x32_bf16 v[116:119], v[190:193], v[212:215], v[116:119]
	v_mfma_f32_16x16x32_bf16 v[108:111], v[198:201], v[212:215], v[108:111]
	v_mfma_f32_16x16x32_bf16 v[100:103], v[190:193], v[220:223], v[100:103]
	v_mfma_f32_16x16x32_bf16 v[92:95], v[198:201], v[220:223], v[92:95]
	v_mfma_f32_16x16x32_bf16 v[84:87], v[190:193], v[228:231], v[84:87]
	v_mfma_f32_16x16x32_bf16 v[76:79], v[198:201], v[228:231], v[76:79]
	v_mfma_f32_16x16x32_bf16 v[68:71], v[190:193], v[236:239], v[68:71]
	v_mfma_f32_16x16x32_bf16 v[64:67], v[198:201], v[236:239], v[64:67]
	s_setprio 0
	s_barrier
; #define PG8_STAGE(bufoff, gbase, voff) do { _Pragma("unroll") for (int _i = 0; _i < 2; ++_i) \
;         __builtin_amdgcn_global_load_lds((const unsigned*)((const char*)(gbase) + (voff)[_i]), (LAS unsigned*)(lds + (bufoff) + ldsw + _i * 8192), 16, 0, 0); } while (0)
; #define PG8_LDA(dst, b, h) do { _Pragma("unroll") for (int m = 0; m < 4; ++m) _Pragma("unroll") for (int k = 0; k < 2; ++k) dst[m][k] = *(const LAS bf16x8*)(lds + PG8_SA(b, h) + aoff + m * 2048 + k * 1024); } while (0)
; #define PG8_MMA(ai, bj, At, Bt) do { __builtin_amdgcn_s_setprio(1); _Pragma("unroll") for (int m = 0; m < 4; ++m) _Pragma("unroll") for (int n = 0; n < 2; ++n) _Pragma("unroll") for (int k = 0; k < 2; ++k) \
;         acc[ai][bj][m][n] = __builtin_amdgcn_mfma_f32_16x16x32_bf16(Bt[n][k], At[m][k], acc[ai][bj][m][n], 0, 0, 0); __builtin_amdgcn_s_setprio(0); } while (0)
; #define PG8_WAIT_V(n) asm volatile("s_waitcnt vmcnt(" #n ")" ::: "memory")
; #define PG8_WAIT_L(n) asm volatile("s_waitcnt lgkmcnt(" #n ")" ::: "memory")
; #define PG8_BAR __builtin_amdgcn_s_barrier()
; #define PG8_SCHED __builtin_amdgcn_sched_barrier(0)
;     DI void operator()(Acc& acc, const Unit& u, int wr, int wc, int fr, int fq, LAS unsigned char* lds) const {
;     ...
;             for (int m = 0; m < 4; ++m) { const int row = u.pm * BM + ai * HALF + wr * 64 + m * 16 + fr;
;                 float rs = 1.0f; if (sumsq) { const f32x4 q4 = *(const f32x4*)(sumsq + (size_t)row * 4); rs = rsqrtf(((q4.x + q4.y) + (q4.z + q4.w)) * (1.0f / DM) + EPS); } float ss = 0.f;
; template <class GEO, class Epi>
; __device__ __forceinline__ void gemm_phase(LAS unsigned char* lds, const Gemm g, const StaticOrder& S, const Epi& E) {
;     ...
;             PG8_WAIT_V(8); PG8_WAIT_L(0); PG8_BAR; PG8_MMA(0, 0, At, B0); PG8_MMA(0, 1, At, B1); PG8_BAR; PG8_SCHED;
;             PG8_LDA(At, 1, 1); PG8_STAGE(PG8_SB(1, 0), b3, voffB); PG8_STAGE(PG8_SB(1, 1), b3 + hstepB, voffB); PG8_STAGE(PG8_SA(1, 0), a3, voffA);
;             PG8_WAIT_V(8); PG8_WAIT_L(0); PG8_BAR; PG8_MMA(1, 0, At, B0); PG8_MMA(1, 1, At, B1); PG8_BAR; PG8_SCHED;
;         }
;         if (wr == 0) PG8_BAR;
;         E(acc, cur, wr, wc, fr, fq, lds);
	s_add_i32 s8, s38, s0
	v_lshl_add_u64 v[160:161], v[160:161], 0, s[28:29]
	s_mov_b32 m0, s8
	ds_read_b128 v[202:205], v183 offset:49152
	ds_read_b128 v[212:215], v183 offset:50176
	ds_read_b128 v[216:219], v183 offset:51200
	ds_read_b128 v[220:223], v183 offset:52224
	ds_read_b128 v[224:227], v183 offset:53248
	ds_read_b128 v[228:231], v183 offset:54272
	ds_read_b128 v[232:235], v183 offset:55296
	ds_read_b128 v[236:239], v183 offset:56320
	global_load_lds_dwordx4 v[160:161], off
	s_add_i32 m0, s8, 0x2000
	s_add_u32 s8, s54, 0x40080
	v_lshl_add_u64 v[160:161], v[170:171], 0, s[28:29]
	s_addc_u32 s9, s55, 0
	s_add_i32 s38, s39, s0
	global_load_lds_dwordx4 v[160:161], off
	v_lshl_add_u64 v[160:161], s[8:9], 0, v[130:131]
	s_mov_b32 m0, s38
	s_nop 0
	global_load_lds_dwordx4 v[160:161], off
	v_lshl_add_u64 v[160:161], s[8:9], 0, v[134:135]
	s_add_i32 m0, s38, 0x2000
	s_nop 0
	global_load_lds_dwordx4 v[160:161], off
	v_lshl_add_u64 v[160:161], v[206:207], 0, s[28:29]
	s_mov_b32 m0, s7
	s_nop 0
	global_load_lds_dwordx4 v[160:161], off
	v_lshl_add_u64 v[160:161], v[240:241], 0, s[28:29]
	s_mov_b32 m0, s12
	s_nop 0
	global_load_lds_dwordx4 v[160:161], off
	s_waitcnt vmcnt(8)
	s_waitcnt lgkmcnt(0)
	s_barrier
	s_setprio 1
	s_waitcnt lgkmcnt(0)
	v_mfma_f32_16x16x32_bf16 v[60:63], v[148:151], v[202:205], v[60:63]
	v_mfma_f32_16x16x32_bf16 v[56:59], v[156:159], v[202:205], v[56:59]
	v_mfma_f32_16x16x32_bf16 v[48:51], v[148:151], v[216:219], v[48:51]
	v_mfma_f32_16x16x32_bf16 v[40:43], v[156:159], v[216:219], v[40:43]
	v_mfma_f32_16x16x32_bf16 v[32:35], v[148:151], v[224:227], v[32:35]
	v_mfma_f32_16x16x32_bf16 v[24:27], v[156:159], v[224:227], v[24:27]
	v_mfma_f32_16x16x32_bf16 v[16:19], v[148:151], v[232:235], v[16:19]
	v_mfma_f32_16x16x32_bf16 v[8:11], v[156:159], v[232:235], v[8:11]
	v_mfma_f32_16x16x32_bf16 v[60:63], v[152:155], v[212:215], v[60:63]
	v_mfma_f32_16x16x32_bf16 v[56:59], v[166:169], v[212:215], v[56:59]
	v_mfma_f32_16x16x32_bf16 v[48:51], v[152:155], v[220:223], v[48:51]
	v_mfma_f32_16x16x32_bf16 v[40:43], v[166:169], v[220:223], v[40:43]
	v_mfma_f32_16x16x32_bf16 v[32:35], v[152:155], v[228:231], v[32:35]
	v_mfma_f32_16x16x32_bf16 v[24:27], v[166:169], v[228:231], v[24:27]
	v_mfma_f32_16x16x32_bf16 v[16:19], v[152:155], v[236:239], v[16:19]
	v_mfma_f32_16x16x32_bf16 v[8:11], v[166:169], v[236:239], v[8:11]
	s_setprio 0
	s_setprio 1
	v_mfma_f32_16x16x32_bf16 v[52:55], v[186:189], v[202:205], v[52:55]
	v_mfma_f32_16x16x32_bf16 v[44:47], v[194:197], v[202:205], v[44:47]
	v_mfma_f32_16x16x32_bf16 v[36:39], v[186:189], v[216:219], v[36:39]
	v_mfma_f32_16x16x32_bf16 v[28:31], v[194:197], v[216:219], v[28:31]
	v_mfma_f32_16x16x32_bf16 v[20:23], v[186:189], v[224:227], v[20:23]
	v_mfma_f32_16x16x32_bf16 v[12:15], v[194:197], v[224:227], v[12:15]
	v_mfma_f32_16x16x32_bf16 v[4:7], v[186:189], v[232:235], v[4:7]
	v_mfma_f32_16x16x32_bf16 v[0:3], v[194:197], v[232:235], v[0:3]
	v_mfma_f32_16x16x32_bf16 v[52:55], v[190:193], v[212:215], v[52:55]
	v_mfma_f32_16x16x32_bf16 v[44:47], v[198:201], v[212:215], v[44:47]
	v_mfma_f32_16x16x32_bf16 v[36:39], v[190:193], v[220:223], v[36:39]
	v_mfma_f32_16x16x32_bf16 v[28:31], v[198:201], v[220:223], v[28:31]
	v_mfma_f32_16x16x32_bf16 v[20:23], v[190:193], v[228:231], v[20:23]
	v_mfma_f32_16x16x32_bf16 v[12:15], v[198:201], v[228:231], v[12:15]
	v_mfma_f32_16x16x32_bf16 v[4:7], v[190:193], v[236:239], v[4:7]
	v_mfma_f32_16x16x32_bf16 v[0:3], v[198:201], v[236:239], v[0:3]
	s_setprio 0
	s_barrier
	s_add_i32 s69, s69, 2
	s_add_u32 s52, s52, 0x100
	s_addc_u32 s53, s53, 0
	s_add_u32 s67, s67, 0x100
	s_addc_u32 s68, s68, 0
	s_cmp_gt_u32 s69, 13
	s_cbranch_scc0 .LBB0_779
	v_lshl_add_u32 v244, s44, 8, v173
	v_ashrrev_i32_e32 v245, 31, v244
	v_lshl_add_u64 v[244:245], v[244:245], 4, s[76:77]
	global_load_dwordx4 v[212:215], v[244:245], off
	global_load_dwordx4 v[216:219], v[244:245], off offset:256
	global_load_dwordx4 v[220:223], v[244:245], off offset:512
	global_load_dwordx4 v[224:227], v[244:245], off offset:768
	global_load_dwordx4 v[228:231], v[244:245], off offset:2048
	global_load_dwordx4 v[232:235], v[244:245], off offset:2304
	global_load_dwordx4 v[236:239], v[244:245], off offset:2560
	global_load_dwordx4 v[240:243], v[244:245], off offset:2816
	s_and_b64 vcc, exec, s[30:31]
	s_cbranch_vccz .LBB0_782
	s_barrier
.LBB0_782:
	v_lshl_add_u32 v166, s44, 8, v173
	v_mov_b32_e32 v182, 1.0
	s_and_b64 vcc, exec, s[22:23]
	v_ashrrev_i32_e32 v167, 31, v166
	v_mov_b32_e32 v186, 1.0
	s_cbranch_vccz .LBB0_784
	v_lshl_add_u64 v[148:149], v[166:167], 4, s[76:77]
	s_waitcnt vmcnt(7)
	v_mov_b32_e32 v148, v212
	v_mov_b32_e32 v149, v213
	v_mov_b32_e32 v150, v214
	v_mov_b32_e32 v151, v215
	v_mov_b32_e32 v152, v149
	v_mov_b32_e32 v153, v150
	v_mov_b32_e32 v149, v151
	v_pk_add_f32 v[148:149], v[152:153], v[148:149]
	s_nop 0
	v_add_f32_e32 v148, v148, v149
	v_fmamk_f32 v148, v148, 0x3a800000, v185
	v_mul_f32_e32 v149, 0x4b800000, v148
	v_cmp_gt_f32_e32 vcc, s62, v148
	s_nop 1
	v_cndmask_b32_e32 v148, v148, v149, vcc
	v_rsq_f32_e32 v148, v148
	s_nop 0
	v_mul_f32_e32 v149, 0x45800000, v148
	v_cndmask_b32_e32 v186, v148, v149, vcc
;     DI void operator()(Acc& acc, const Unit& u, int wr, int wc, int fr, int fq, LAS unsigned char* lds) const {
;     ...
;             for (int m = 0; m < 4; ++m) { const int row = u.pm * BM + ai * HALF + wr * 64 + m * 16 + fr;
;                 float rs = 1.0f; if (sumsq) { const f32x4 q4 = *(const f32x4*)(sumsq + (size_t)row * 4); rs = rsqrtf(((q4.x + q4.y) + (q4.z + q4.w)) * (1.0f / DM) + EPS); } float ss = 0.f;
.LBB0_784:
	v_cndmask_b32_e64 v148, 0, 1, s[22:23]
	v_or_b32_e32 v160, 16, v166
	v_cmp_ne_u32_e64 s[44:45], 1, v148
	s_andn2_b64 vcc, exec, s[22:23]
	v_ashrrev_i32_e32 v161, 31, v160
	s_cbranch_vccnz .LBB0_786
	v_lshl_add_u64 v[148:149], v[160:161], 4, s[76:77]
	s_waitcnt vmcnt(6)
	v_mov_b32_e32 v148, v216
	v_mov_b32_e32 v149, v217
	v_mov_b32_e32 v150, v218
	v_mov_b32_e32 v151, v219
	v_mov_b32_e32 v152, v149
	v_mov_b32_e32 v153, v150
	v_mov_b32_e32 v149, v151
	v_pk_add_f32 v[148:149], v[152:153], v[148:149]
	s_nop 0
	v_add_f32_e32 v148, v148, v149
	v_fmamk_f32 v148, v148, 0x3a800000, v185
	v_mul_f32_e32 v149, 0x4b800000, v148
	v_cmp_gt_f32_e32 vcc, s62, v148
	s_nop 1
	v_cndmask_b32_e32 v148, v148, v149, vcc
	v_rsq_f32_e32 v148, v148
	s_nop 0
	v_mul_f32_e32 v149, 0x45800000, v148
	v_cndmask_b32_e32 v182, v148, v149, vcc
.LBB0_786:
	v_or_b32_e32 v158, 32, v166
	v_mov_b32_e32 v178, 1.0
	s_and_b64 vcc, exec, s[44:45]
	v_ashrrev_i32_e32 v159, 31, v158
	v_mov_b32_e32 v184, 1.0
	s_cbranch_vccnz .LBB0_788
	v_lshl_add_u64 v[148:149], v[158:159], 4, s[76:77]
	s_waitcnt vmcnt(5)
	v_mov_b32_e32 v148, v220
	v_mov_b32_e32 v149, v221
	v_mov_b32_e32 v150, v222
	v_mov_b32_e32 v151, v223
	v_mov_b32_e32 v152, v149
	v_mov_b32_e32 v153, v150
	v_mov_b32_e32 v149, v151
	v_pk_add_f32 v[148:149], v[152:153], v[148:149]
	s_nop 0
	v_add_f32_e32 v148, v148, v149
	v_fmamk_f32 v148, v148, 0x3a800000, v185
	v_mul_f32_e32 v149, 0x4b800000, v148
	v_cmp_gt_f32_e32 vcc, s62, v148
	s_nop 1
	v_cndmask_b32_e32 v148, v148, v149, vcc
	v_rsq_f32_e32 v148, v148
	s_nop 0
	v_mul_f32_e32 v149, 0x45800000, v148
	v_cndmask_b32_e32 v184, v148, v149, vcc
.LBB0_788:
	v_or_b32_e32 v156, 48, v166
	s_and_b64 vcc, exec, s[44:45]
	v_ashrrev_i32_e32 v157, 31, v156
	s_cbranch_vccnz .LBB0_790
	v_lshl_add_u64 v[148:149], v[156:157], 4, s[76:77]
	s_waitcnt vmcnt(4)
	v_mov_b32_e32 v148, v224
	v_mov_b32_e32 v149, v225
	v_mov_b32_e32 v150, v226
	v_mov_b32_e32 v151, v227
	v_mov_b32_e32 v152, v149
	v_mov_b32_e32 v153, v150
	v_mov_b32_e32 v149, v151
	v_pk_add_f32 v[148:149], v[152:153], v[148:149]
	s_nop 0
	v_add_f32_e32 v148, v148, v149
	v_fmamk_f32 v148, v148, 0x3a800000, v185
	v_mul_f32_e32 v149, 0x4b800000, v148
	v_cmp_gt_f32_e32 vcc, s62, v148
	s_nop 1
	v_cndmask_b32_e32 v148, v148, v149, vcc
	v_rsq_f32_e32 v148, v148
	s_nop 0
	v_mul_f32_e32 v149, 0x45800000, v148
	v_cndmask_b32_e32 v178, v148, v149, vcc
.LBB0_790:
	v_add_u32_e32 v154, 0x80, v166
	v_mov_b32_e32 v174, 1.0
	s_and_b64 vcc, exec, s[44:45]
	v_ashrrev_i32_e32 v155, 31, v154
	v_mov_b32_e32 v180, 1.0
	s_cbranch_vccnz .LBB0_792
	v_lshl_add_u64 v[148:149], v[154:155], 4, s[76:77]
	s_waitcnt vmcnt(3)
	v_mov_b32_e32 v148, v228
	v_mov_b32_e32 v149, v229
	v_mov_b32_e32 v150, v230
	v_mov_b32_e32 v151, v231
	v_mov_b32_e32 v152, v149
	v_mov_b32_e32 v153, v150
	v_mov_b32_e32 v149, v151
	v_pk_add_f32 v[148:149], v[152:153], v[148:149]
	s_nop 0
	v_add_f32_e32 v148, v148, v149
	v_fmamk_f32 v148, v148, 0x3a800000, v185
	v_mul_f32_e32 v149, 0x4b800000, v148
	v_cmp_gt_f32_e32 vcc, s62, v148
	s_nop 1
	v_cndmask_b32_e32 v148, v148, v149, vcc
	v_rsq_f32_e32 v148, v148
	s_nop 0
	v_mul_f32_e32 v149, 0x45800000, v148
	v_cndmask_b32_e32 v180, v148, v149, vcc
.LBB0_792:
	v_add_u32_e32 v152, 0x90, v166
	s_and_b64 vcc, exec, s[44:45]
	v_ashrrev_i32_e32 v153, 31, v152
	s_cbranch_vccnz .LBB0_794
	v_lshl_add_u64 v[148:149], v[152:153], 4, s[76:77]
	s_waitcnt vmcnt(2)
	v_mov_b32_e32 v148, v232
	v_mov_b32_e32 v149, v233
	v_mov_b32_e32 v150, v234
	v_mov_b32_e32 v151, v235
	v_mov_b32_e32 v168, v149
	v_mov_b32_e32 v169, v150
	v_mov_b32_e32 v149, v151
	v_pk_add_f32 v[148:149], v[168:169], v[148:149]
	s_nop 0
	v_add_f32_e32 v148, v148, v149
	v_fmamk_f32 v148, v148, 0x3a800000, v185
	v_mul_f32_e32 v149, 0x4b800000, v148
	v_cmp_gt_f32_e32 vcc, s62, v148
	s_nop 1
	v_cndmask_b32_e32 v148, v148, v149, vcc
	v_rsq_f32_e32 v148, v148
	s_nop 0
	v_mul_f32_e32 v149, 0x45800000, v148
	v_cndmask_b32_e32 v174, v148, v149, vcc
.LBB0_794:
	v_add_u32_e32 v150, 0xa0, v166
	v_mov_b32_e32 v172, 1.0
	s_and_b64 vcc, exec, s[44:45]
	v_ashrrev_i32_e32 v151, 31, v150
	v_mov_b32_e32 v176, 1.0
	s_cbranch_vccnz .LBB0_796
	v_lshl_add_u64 v[148:149], v[150:151], 4, s[76:77]
	s_waitcnt vmcnt(1)
	v_mov_b32_e32 v168, v236
	v_mov_b32_e32 v169, v237
	v_mov_b32_e32 v170, v238
	v_mov_b32_e32 v171, v239
	v_mov_b32_e32 v148, v169
	v_mov_b32_e32 v149, v170
	v_mov_b32_e32 v169, v171
	v_pk_add_f32 v[148:149], v[148:149], v[168:169]
	s_nop 0
	v_add_f32_e32 v148, v148, v149
	v_fmamk_f32 v148, v148, 0x3a800000, v185
	v_mul_f32_e32 v149, 0x4b800000, v148
	v_cmp_gt_f32_e32 vcc, s62, v148
	s_nop 1
	v_cndmask_b32_e32 v148, v148, v149, vcc
	v_rsq_f32_e32 v148, v148
	s_nop 0
	v_mul_f32_e32 v149, 0x45800000, v148
	v_cndmask_b32_e32 v176, v148, v149, vcc
.LBB0_796:
	v_add_u32_e32 v148, 0xb0, v166
	s_and_b64 vcc, exec, s[44:45]
	v_ashrrev_i32_e32 v149, 31, v148
	s_cbranch_vccnz .LBB0_798
	v_lshl_add_u64 v[168:169], v[148:149], 4, s[76:77]
	s_waitcnt vmcnt(0)
	v_mov_b32_e32 v168, v240
	v_mov_b32_e32 v169, v241
	v_mov_b32_e32 v170, v242
	v_mov_b32_e32 v171, v243
	v_mov_b32_e32 v188, v169
	v_mov_b32_e32 v189, v170
	v_mov_b32_e32 v169, v171
	v_pk_add_f32 v[168:169], v[188:189], v[168:169]
	s_nop 0
	v_add_f32_e32 v168, v168, v169
	v_fmamk_f32 v168, v168, 0x3a800000, v185
	v_mul_f32_e32 v169, 0x4b800000, v168
	v_cmp_gt_f32_e32 vcc, s62, v168
	s_nop 1
	v_cndmask_b32_e32 v168, v168, v169, vcc
	v_rsq_f32_e32 v168, v168
	s_nop 0
	v_mul_f32_e32 v169, 0x45800000, v168
	v_cndmask_b32_e32 v172, v168, v169, vcc

; #define LAS __attribute__((address_space(3)))
; DI unsigned pk2(float lo, float hi) { f32x2 v = {lo, hi}; bf16x2_t b = __builtin_convertvector(v, bf16x2_t); return __builtin_bit_cast(unsigned, b); }
; #define BAR_LDS() do { asm volatile("s_waitcnt lgkmcnt(0)" ::: "memory"); __builtin_amdgcn_s_barrier(); asm volatile("" ::: "memory"); } while (0)
; template <bool ISMAX> DI void tile_row_reduce(float (&p)[2][4], LAS float* red, int wr, int wc, int fr, int fq) {
;     ...
;     BAR_LDS();
; #pragma unroll
;     for (int ai = 0; ai < 2; ++ai)
; #pragma unroll
;         for (int m = 0; m < 4; ++m) { const f32x4 q = *(const LAS f32x4*)(red + (ai * 128 + wr * 64 + m * 16 + fr) * 4);
;             p[ai][m] = ISMAX ? fmaxf(fmaxf(q.x, q.y), fmaxf(q.z, q.w)) : (q.x + q.y) + (q.z + q.w); }
;     DI void operator()(Acc& acc, const Unit& u, int wr, int wc, int fr, int fq, LAS unsigned char* lds) const {
;     ...
;         const int cin = wc * 32 + 8 * fq;
; #pragma unroll
;         for (int ai = 0; ai < 2; ++ai)
; #pragma unroll
;             for (int m = 0; m < 4; ++m) { const int row = u.pm * BM + ai * HALF + wr * 64 + m * 16 + fr; const float rn = rsqrtf(part[ai][m] * (1.0f / 256.0f) + EPS) * scale;
;                 bf16_t* rowp = O + (size_t)row * DM + u.pn * BM + cin;
; #pragma unroll
;                 for (int bj = 0; bj < 2; ++bj) { const f32x4 g0 = *(const f32x4*)(gain + bj * HALF + cin), g1 = *(const f32x4*)(gain + bj * HALF + cin + 4);
;                     const f32x4 v0 = acc[ai][bj][m][0] * rn * g0, v1 = acc[ai][bj][m][1] * rn * g1;
;                     u32x4 w; w.x = pk2(v0.x, v0.y); w.y = pk2(v0.z, v0.w); w.z = pk2(v1.x, v1.y); w.w = pk2(v1.z, v1.w); __builtin_nontemporal_store(w, (u32x4*)(rowp + bj * HALF)); } }
.LBB0_814:
	s_or_b64 exec, exec, s[44:45]
	s_waitcnt lgkmcnt(0)
	s_barrier
	global_load_dwordx4 v[212:215], v[138:139], off
	global_load_dwordx4 v[216:219], v[138:139], off offset:16
	global_load_dwordx4 v[220:223], v[138:139], off offset:512
	global_load_dwordx4 v[224:227], v[138:139], off offset:528
	v_add_u32_e32 v16, s13, v177
	v_add_u32_e32 v172, s19, v177
	ds_read_b128 v[194:197], v16
	ds_read_b128 v[198:201], v172
	v_lshlrev_b64 v[18:19], 11, v[166:167]
	s_mov_b32 s16, 0x358637bd
	s_waitcnt lgkmcnt(0)
	v_mov_b64_e32 v[16:17], s[16:17]
	v_mov_b32_e32 v166, v195
	v_mov_b32_e32 v167, v196
	v_mov_b32_e32 v195, v197
	v_mov_b32_e32 v196, v199
	v_mov_b32_e32 v197, v200
	v_mov_b32_e32 v199, v201
	v_pk_add_f32 v[166:167], v[166:167], v[194:195]
	v_pk_add_f32 v[194:195], v[196:197], v[198:199]
	v_mov_b32_e32 v197, v166
	v_mov_b32_e32 v196, v194
	v_mov_b32_e32 v166, v195
	v_pk_add_f32 v[166:167], v[196:197], v[166:167]
	s_lshl_b32 s8, s65, 8
	v_pk_fma_f32 v[194:195], v[166:167], s[34:35], v[16:17] op_sel_hi:[1,0,0]
	s_ashr_i32 s9, s8, 31
	v_mul_f32_e32 v166, 0x4b800000, v195
	v_cmp_gt_f32_e32 vcc, s62, v195
	v_lshl_add_u64 v[18:19], s[14:15], 0, v[18:19]
	s_lshl_b64 s[44:45], s[8:9], 1
	v_cndmask_b32_e32 v166, v195, v166, vcc
	v_rsq_f32_e32 v166, v166
	v_lshl_add_u64 v[18:19], v[18:19], 0, s[44:45]
	v_lshl_add_u64 v[18:19], v[18:19], 0, v[136:137]
	v_mul_f32_e32 v167, 0x45800000, v166
	v_cndmask_b32_e32 v166, v166, v167, vcc
	v_mul_f32_e32 v172, 0x3d800000, v166
	v_pk_mul_f32 v[166:167], v[168:169], v[172:173] op_sel_hi:[1,0]
	v_pk_mul_f32 v[126:127], v[126:127], v[172:173] op_sel_hi:[1,0]
	v_pk_mul_f32 v[168:169], v[170:171], v[172:173] op_sel_hi:[1,0]
	v_pk_mul_f32 v[124:125], v[124:125], v[172:173] op_sel_hi:[1,0]
	v_pk_mul_f32 v[120:121], v[120:121], v[172:173] op_sel_hi:[1,0]
	v_pk_mul_f32 v[118:119], v[118:119], v[172:173] op_sel_hi:[1,0]
	v_pk_mul_f32 v[122:123], v[122:123], v[172:173] op_sel_hi:[1,0]
	v_pk_mul_f32 v[116:117], v[116:117], v[172:173] op_sel_hi:[1,0]
	v_cmp_gt_f32_e32 vcc, s62, v194
	s_waitcnt vmcnt(0)
	v_pk_mul_f32 v[126:127], v[214:215], v[126:127]
	v_pk_mul_f32 v[166:167], v[212:213], v[166:167]
	v_pk_mul_f32 v[170:171], v[218:219], v[124:125]
	v_pk_mul_f32 v[168:169], v[216:217], v[168:169]
	v_cvt_pk_bf16_f32 v124, v166, v167
	v_cvt_pk_bf16_f32 v125, v126, v127
	v_cvt_pk_bf16_f32 v126, v168, v169
	v_cvt_pk_bf16_f32 v127, v170, v171
	global_store_dwordx4 v[18:19], v[124:127], off nt
	s_nop 1
	s_nop 0
	v_pk_mul_f32 v[118:119], v[222:223], v[118:119]
	v_pk_mul_f32 v[120:121], v[220:221], v[120:121]
	v_pk_mul_f32 v[124:125], v[226:227], v[116:117]
	v_pk_mul_f32 v[122:123], v[224:225], v[122:123]
	v_cvt_pk_bf16_f32 v116, v120, v121
	v_cvt_pk_bf16_f32 v117, v118, v119
	v_cvt_pk_bf16_f32 v118, v122, v123
	v_cvt_pk_bf16_f32 v119, v124, v125
	global_store_dwordx4 v[18:19], v[116:119], off offset:256 nt
	s_nop 1
	s_nop 0
	v_mul_f32_e32 v124, 0x4b800000, v194
	v_cndmask_b32_e32 v124, v194, v124, vcc
	v_rsq_f32_e32 v124, v124
	v_lshlrev_b64 v[18:19], 11, v[160:161]
	v_lshl_add_u64 v[18:19], s[14:15], 0, v[18:19]
	v_lshl_add_u64 v[18:19], v[18:19], 0, s[44:45]
	v_mul_f32_e32 v125, 0x45800000, v124
	v_cndmask_b32_e32 v124, v124, v125, vcc
	v_mul_f32_e32 v124, 0x3d800000, v124
	v_pk_mul_f32 v[112:113], v[112:113], v[124:125] op_sel_hi:[1,0]
	v_pk_mul_f32 v[108:109], v[108:109], v[124:125] op_sel_hi:[1,0]
	v_pk_mul_f32 v[114:115], v[114:115], v[124:125] op_sel_hi:[1,0]
	v_pk_mul_f32 v[110:111], v[110:111], v[124:125] op_sel_hi:[1,0]
	v_lshl_add_u64 v[18:19], v[18:19], 0, v[136:137]
	v_pk_mul_f32 v[104:105], v[104:105], v[124:125] op_sel_hi:[1,0]
	v_pk_mul_f32 v[102:103], v[102:103], v[124:125] op_sel_hi:[1,0]
	v_pk_mul_f32 v[106:107], v[106:107], v[124:125] op_sel_hi:[1,0]
	v_pk_mul_f32 v[100:101], v[100:101], v[124:125] op_sel_hi:[1,0]
	v_pk_mul_f32 v[118:119], v[214:215], v[108:109]
	v_pk_mul_f32 v[108:109], v[212:213], v[112:113]
	v_pk_mul_f32 v[112:113], v[218:219], v[110:111]
	v_pk_mul_f32 v[110:111], v[216:217], v[114:115]
	v_cvt_pk_bf16_f32 v108, v108, v109
	v_cvt_pk_bf16_f32 v109, v118, v119
	v_cvt_pk_bf16_f32 v110, v110, v111
	v_cvt_pk_bf16_f32 v111, v112, v113
	global_store_dwordx4 v[18:19], v[108:111], off nt
	s_nop 1
	s_nop 0
	v_pk_mul_f32 v[102:103], v[102:103], v[222:223]
	v_pk_mul_f32 v[104:105], v[104:105], v[220:221]
	v_pk_mul_f32 v[108:109], v[100:101], v[226:227]
	v_pk_mul_f32 v[106:107], v[106:107], v[224:225]
	v_cvt_pk_bf16_f32 v100, v104, v105
	v_cvt_pk_bf16_f32 v101, v102, v103
	v_cvt_pk_bf16_f32 v102, v106, v107
	v_cvt_pk_bf16_f32 v103, v108, v109
	global_store_dwordx4 v[18:19], v[100:103], off offset:256 nt
	s_nop 1
	s_nop 0
	v_add_u32_e32 v18, s33, v177
	ds_read_b128 v[108:111], v18
	v_add_u32_e32 v18, s35, v177
	ds_read_b128 v[112:115], v18
	v_lshlrev_b64 v[18:19], 11, v[158:159]
	v_lshl_add_u64 v[18:19], s[14:15], 0, v[18:19]
	s_waitcnt lgkmcnt(1)
	v_mov_b32_e32 v116, v109
	v_mov_b32_e32 v117, v110
	v_mov_b32_e32 v109, v111
	s_waitcnt lgkmcnt(0)
; #define LAS __attribute__((address_space(3)))
; DI unsigned pk2(float lo, float hi) { f32x2 v = {lo, hi}; bf16x2_t b = __builtin_convertvector(v, bf16x2_t); return __builtin_bit_cast(unsigned, b); }
; #define BAR_LDS() do { asm volatile("s_waitcnt lgkmcnt(0)" ::: "memory"); __builtin_amdgcn_s_barrier(); asm volatile("" ::: "memory"); } while (0)
; template <bool ISMAX> DI void tile_row_reduce(float (&p)[2][4], LAS float* red, int wr, int wc, int fr, int fq) {
;     ...
;     BAR_LDS();
; #pragma unroll
;     for (int ai = 0; ai < 2; ++ai)
; #pragma unroll
;         for (int m = 0; m < 4; ++m) { const f32x4 q = *(const LAS f32x4*)(red + (ai * 128 + wr * 64 + m * 16 + fr) * 4);
;             p[ai][m] = ISMAX ? fmaxf(fmaxf(q.x, q.y), fmaxf(q.z, q.w)) : (q.x + q.y) + (q.z + q.w); }
;     DI void operator()(Acc& acc, const Unit& u, int wr, int wc, int fr, int fq, LAS unsigned char* lds) const {
;     ...
;         const int cin = wc * 32 + 8 * fq;
; #pragma unroll
;         for (int ai = 0; ai < 2; ++ai)
; #pragma unroll
;             for (int m = 0; m < 4; ++m) { const int row = u.pm * BM + ai * HALF + wr * 64 + m * 16 + fr; const float rn = rsqrtf(part[ai][m] * (1.0f / 256.0f) + EPS) * scale;
;                 bf16_t* rowp = O + (size_t)row * DM + u.pn * BM + cin;
; #pragma unroll
;                 for (int bj = 0; bj < 2; ++bj) { const f32x4 g0 = *(const f32x4*)(gain + bj * HALF + cin), g1 = *(const f32x4*)(gain + bj * HALF + cin + 4);
;                     const f32x4 v0 = acc[ai][bj][m][0] * rn * g0, v1 = acc[ai][bj][m][1] * rn * g1;
;                     u32x4 w; w.x = pk2(v0.x, v0.y); w.y = pk2(v0.z, v0.w); w.z = pk2(v1.x, v1.y); w.w = pk2(v1.z, v1.w); __builtin_nontemporal_store(w, (u32x4*)(rowp + bj * HALF)); } }
	v_mov_b32_e32 v110, v113
	v_mov_b32_e32 v111, v114
	v_mov_b32_e32 v113, v115
	v_pk_add_f32 v[108:109], v[116:117], v[108:109]
	v_pk_add_f32 v[110:111], v[110:111], v[112:113]
	v_mov_b32_e32 v113, v108
	v_mov_b32_e32 v112, v110
	v_mov_b32_e32 v108, v111
	v_pk_add_f32 v[108:109], v[112:113], v[108:109]
	v_lshl_add_u64 v[18:19], v[18:19], 0, s[44:45]
	v_pk_fma_f32 v[108:109], v[108:109], s[34:35], v[16:17] op_sel_hi:[1,0,0]
	v_lshl_add_u64 v[18:19], v[18:19], 0, v[136:137]
	v_mul_f32_e32 v110, 0x4b800000, v109
	v_cmp_gt_f32_e32 vcc, s62, v109
	s_nop 1
	v_cndmask_b32_e32 v109, v109, v110, vcc
	v_rsq_f32_e32 v109, v109
	s_nop 0
	v_mul_f32_e32 v110, 0x45800000, v109
	v_cndmask_b32_e32 v109, v109, v110, vcc
	v_mul_f32_e32 v110, 0x3d800000, v109
	v_pk_mul_f32 v[96:97], v[96:97], v[110:111] op_sel_hi:[1,0]
	v_pk_mul_f32 v[92:93], v[92:93], v[110:111] op_sel_hi:[1,0]
	v_pk_mul_f32 v[98:99], v[98:99], v[110:111] op_sel_hi:[1,0]
	v_pk_mul_f32 v[94:95], v[94:95], v[110:111] op_sel_hi:[1,0]
	v_pk_mul_f32 v[88:89], v[88:89], v[110:111] op_sel_hi:[1,0]
	v_pk_mul_f32 v[86:87], v[86:87], v[110:111] op_sel_hi:[1,0]
	v_pk_mul_f32 v[90:91], v[90:91], v[110:111] op_sel_hi:[1,0]
	v_pk_mul_f32 v[84:85], v[84:85], v[110:111] op_sel_hi:[1,0]
	v_cmp_gt_f32_e32 vcc, s62, v108
	v_pk_mul_f32 v[102:103], v[92:93], v[214:215]
	v_pk_mul_f32 v[92:93], v[96:97], v[212:213]
	v_pk_mul_f32 v[96:97], v[94:95], v[218:219]
	v_pk_mul_f32 v[94:95], v[98:99], v[216:217]
	v_cvt_pk_bf16_f32 v92, v92, v93
	v_cvt_pk_bf16_f32 v93, v102, v103
	v_cvt_pk_bf16_f32 v94, v94, v95
	v_cvt_pk_bf16_f32 v95, v96, v97
	global_store_dwordx4 v[18:19], v[92:95], off nt
	s_nop 1
	s_nop 0
	v_pk_mul_f32 v[86:87], v[86:87], v[222:223]
	v_pk_mul_f32 v[88:89], v[88:89], v[220:221]
	v_pk_mul_f32 v[92:93], v[84:85], v[226:227]
	v_pk_mul_f32 v[90:91], v[90:91], v[224:225]
	v_cvt_pk_bf16_f32 v84, v88, v89
	v_cvt_pk_bf16_f32 v85, v86, v87
	v_cvt_pk_bf16_f32 v86, v90, v91
	v_cvt_pk_bf16_f32 v87, v92, v93
	global_store_dwordx4 v[18:19], v[84:87], off offset:256 nt
	s_nop 1
	s_nop 0
	v_mul_f32_e32 v92, 0x4b800000, v108
	v_cndmask_b32_e32 v92, v108, v92, vcc
	v_rsq_f32_e32 v92, v92
	v_lshlrev_b64 v[18:19], 11, v[156:157]
	v_lshl_add_u64 v[18:19], s[14:15], 0, v[18:19]
	v_lshl_add_u64 v[18:19], v[18:19], 0, s[44:45]
	v_mul_f32_e32 v93, 0x45800000, v92
	v_cndmask_b32_e32 v92, v92, v93, vcc
	v_mul_f32_e32 v92, 0x3d800000, v92
	v_pk_mul_f32 v[80:81], v[80:81], v[92:93] op_sel_hi:[1,0]
	v_pk_mul_f32 v[76:77], v[76:77], v[92:93] op_sel_hi:[1,0]
	v_pk_mul_f32 v[82:83], v[82:83], v[92:93] op_sel_hi:[1,0]
	v_pk_mul_f32 v[78:79], v[78:79], v[92:93] op_sel_hi:[1,0]
	v_lshl_add_u64 v[18:19], v[18:19], 0, v[136:137]
	v_pk_mul_f32 v[72:73], v[72:73], v[92:93] op_sel_hi:[1,0]
	v_pk_mul_f32 v[70:71], v[70:71], v[92:93] op_sel_hi:[1,0]
	v_pk_mul_f32 v[74:75], v[74:75], v[92:93] op_sel_hi:[1,0]
	v_pk_mul_f32 v[68:69], v[68:69], v[92:93] op_sel_hi:[1,0]
	v_pk_mul_f32 v[86:87], v[76:77], v[214:215]
	v_pk_mul_f32 v[76:77], v[80:81], v[212:213]
	v_pk_mul_f32 v[80:81], v[78:79], v[218:219]
	v_pk_mul_f32 v[78:79], v[82:83], v[216:217]
	v_cvt_pk_bf16_f32 v76, v76, v77
	v_cvt_pk_bf16_f32 v77, v86, v87
	v_cvt_pk_bf16_f32 v78, v78, v79
	v_cvt_pk_bf16_f32 v79, v80, v81
	global_store_dwordx4 v[18:19], v[76:79], off nt
	s_nop 1
	s_nop 0
	v_pk_mul_f32 v[70:71], v[70:71], v[222:223]
	v_pk_mul_f32 v[72:73], v[72:73], v[220:221]
	v_pk_mul_f32 v[76:77], v[68:69], v[226:227]
	v_pk_mul_f32 v[74:75], v[74:75], v[224:225]
	v_cvt_pk_bf16_f32 v68, v72, v73
	v_cvt_pk_bf16_f32 v69, v70, v71
	v_cvt_pk_bf16_f32 v70, v74, v75
	v_cvt_pk_bf16_f32 v71, v76, v77
	global_store_dwordx4 v[18:19], v[68:71], off offset:256 nt
	s_nop 1
	s_nop 0
	v_add_u32_e32 v18, s36, v177
	ds_read_b128 v[76:79], v18
	v_add_u32_e32 v18, s37, v177
	ds_read_b128 v[80:83], v18
	v_lshlrev_b64 v[18:19], 11, v[154:155]
	v_lshl_add_u64 v[18:19], s[14:15], 0, v[18:19]
	s_waitcnt lgkmcnt(1)
	v_mov_b32_e32 v84, v77
	v_mov_b32_e32 v85, v78
	v_mov_b32_e32 v77, v79
	s_waitcnt lgkmcnt(0)
	v_mov_b32_e32 v78, v81
	v_mov_b32_e32 v79, v82
	v_mov_b32_e32 v81, v83
	v_pk_add_f32 v[76:77], v[84:85], v[76:77]
	v_pk_add_f32 v[78:79], v[78:79], v[80:81]
	v_mov_b32_e32 v81, v76
	v_mov_b32_e32 v80, v78
	v_mov_b32_e32 v76, v79
	v_pk_add_f32 v[76:77], v[80:81], v[76:77]
	v_lshl_add_u64 v[18:19], v[18:19], 0, s[44:45]
	v_pk_fma_f32 v[76:77], v[76:77], s[34:35], v[16:17] op_sel_hi:[1,0,0]
	v_lshl_add_u64 v[18:19], v[18:19], 0, v[136:137]
	v_mul_f32_e32 v78, 0x4b800000, v77
	v_cmp_gt_f32_e32 vcc, s62, v77
	s_nop 1
	v_cndmask_b32_e32 v77, v77, v78, vcc
	v_rsq_f32_e32 v77, v77
	s_nop 0
	v_mul_f32_e32 v78, 0x45800000, v77
	v_cndmask_b32_e32 v77, v77, v78, vcc
	v_mul_f32_e32 v78, 0x3d800000, v77
	v_pk_mul_f32 v[64:65], v[64:65], v[78:79] op_sel_hi:[1,0]
	v_pk_mul_f32 v[62:63], v[62:63], v[78:79] op_sel_hi:[1,0]
	v_pk_mul_f32 v[66:67], v[66:67], v[78:79] op_sel_hi:[1,0]
	v_pk_mul_f32 v[60:61], v[60:61], v[78:79] op_sel_hi:[1,0]
	v_pk_mul_f32 v[56:57], v[56:57], v[78:79] op_sel_hi:[1,0]
	v_pk_mul_f32 v[54:55], v[54:55], v[78:79] op_sel_hi:[1,0]
	v_pk_mul_f32 v[58:59], v[58:59], v[78:79] op_sel_hi:[1,0]
	v_pk_mul_f32 v[52:53], v[52:53], v[78:79] op_sel_hi:[1,0]
	v_cmp_gt_f32_e32 vcc, s62, v76
	v_pk_mul_f32 v[62:63], v[62:63], v[214:215]
	v_pk_mul_f32 v[64:65], v[64:65], v[212:213]
	v_pk_mul_f32 v[68:69], v[60:61], v[218:219]
	v_pk_mul_f32 v[66:67], v[66:67], v[216:217]
	v_cvt_pk_bf16_f32 v60, v64, v65
	v_cvt_pk_bf16_f32 v61, v62, v63
	v_cvt_pk_bf16_f32 v62, v66, v67
	v_cvt_pk_bf16_f32 v63, v68, v69
	global_store_dwordx4 v[18:19], v[60:63], off nt
	s_nop 1
	s_nop 0
	v_pk_mul_f32 v[54:55], v[54:55], v[222:223]
; DI unsigned pk2(float lo, float hi) { f32x2 v = {lo, hi}; bf16x2_t b = __builtin_convertvector(v, bf16x2_t); return __builtin_bit_cast(unsigned, b); }
;     DI void operator()(Acc& acc, const Unit& u, int wr, int wc, int fr, int fq, LAS unsigned char* lds) const {
;     ...
;         const int cin = wc * 32 + 8 * fq;
; #pragma unroll
;         for (int ai = 0; ai < 2; ++ai)
; #pragma unroll
;             for (int m = 0; m < 4; ++m) { const int row = u.pm * BM + ai * HALF + wr * 64 + m * 16 + fr; const float rn = rsqrtf(part[ai][m] * (1.0f / 256.0f) + EPS) * scale;
;                 bf16_t* rowp = O + (size_t)row * DM + u.pn * BM + cin;
; #pragma unroll
;                 for (int bj = 0; bj < 2; ++bj) { const f32x4 g0 = *(const f32x4*)(gain + bj * HALF + cin), g1 = *(const f32x4*)(gain + bj * HALF + cin + 4);
;                     const f32x4 v0 = acc[ai][bj][m][0] * rn * g0, v1 = acc[ai][bj][m][1] * rn * g1;
;                     u32x4 w; w.x = pk2(v0.x, v0.y); w.y = pk2(v0.z, v0.w); w.z = pk2(v1.x, v1.y); w.w = pk2(v1.z, v1.w); __builtin_nontemporal_store(w, (u32x4*)(rowp + bj * HALF)); } }
	v_pk_mul_f32 v[56:57], v[56:57], v[220:221]
	v_pk_mul_f32 v[60:61], v[52:53], v[226:227]
	v_pk_mul_f32 v[58:59], v[58:59], v[224:225]
	v_cvt_pk_bf16_f32 v52, v56, v57
	v_cvt_pk_bf16_f32 v53, v54, v55
	v_cvt_pk_bf16_f32 v54, v58, v59
	v_cvt_pk_bf16_f32 v55, v60, v61
	global_store_dwordx4 v[18:19], v[52:55], off offset:256 nt
	s_nop 1
	s_nop 0
	v_mul_f32_e32 v60, 0x4b800000, v76
	v_cndmask_b32_e32 v60, v76, v60, vcc
	v_rsq_f32_e32 v60, v60
	v_lshlrev_b64 v[18:19], 11, v[152:153]
	v_lshl_add_u64 v[18:19], s[14:15], 0, v[18:19]
	v_lshl_add_u64 v[18:19], v[18:19], 0, s[44:45]
	v_mul_f32_e32 v61, 0x45800000, v60
	v_cndmask_b32_e32 v60, v60, v61, vcc
	v_mul_f32_e32 v60, 0x3d800000, v60
	v_pk_mul_f32 v[48:49], v[48:49], v[60:61] op_sel_hi:[1,0]
	v_pk_mul_f32 v[44:45], v[44:45], v[60:61] op_sel_hi:[1,0]
	v_pk_mul_f32 v[50:51], v[50:51], v[60:61] op_sel_hi:[1,0]
	v_pk_mul_f32 v[46:47], v[46:47], v[60:61] op_sel_hi:[1,0]
	v_lshl_add_u64 v[18:19], v[18:19], 0, v[136:137]
	v_pk_mul_f32 v[40:41], v[40:41], v[60:61] op_sel_hi:[1,0]
	v_pk_mul_f32 v[38:39], v[38:39], v[60:61] op_sel_hi:[1,0]
	v_pk_mul_f32 v[42:43], v[42:43], v[60:61] op_sel_hi:[1,0]
	v_pk_mul_f32 v[36:37], v[36:37], v[60:61] op_sel_hi:[1,0]
	v_pk_mul_f32 v[54:55], v[44:45], v[214:215]
	v_pk_mul_f32 v[44:45], v[48:49], v[212:213]
	v_pk_mul_f32 v[48:49], v[46:47], v[218:219]
	v_pk_mul_f32 v[46:47], v[50:51], v[216:217]
	v_cvt_pk_bf16_f32 v44, v44, v45
	v_cvt_pk_bf16_f32 v45, v54, v55
	v_cvt_pk_bf16_f32 v46, v46, v47
	v_cvt_pk_bf16_f32 v47, v48, v49
	global_store_dwordx4 v[18:19], v[44:47], off nt
	s_nop 1
	s_nop 0
	v_pk_mul_f32 v[38:39], v[38:39], v[222:223]
	v_pk_mul_f32 v[40:41], v[40:41], v[220:221]
	v_pk_mul_f32 v[44:45], v[36:37], v[226:227]
	v_pk_mul_f32 v[42:43], v[42:43], v[224:225]
	v_cvt_pk_bf16_f32 v36, v40, v41
	v_cvt_pk_bf16_f32 v37, v38, v39
	v_cvt_pk_bf16_f32 v38, v42, v43
	v_cvt_pk_bf16_f32 v39, v44, v45
	global_store_dwordx4 v[18:19], v[36:39], off offset:256 nt
	s_nop 1
	s_nop 0
	v_add_u32_e32 v18, s58, v177
	ds_read_b128 v[44:47], v18
	v_add_u32_e32 v18, s59, v177
	ds_read_b128 v[48:51], v18
	v_lshlrev_b64 v[18:19], 11, v[150:151]
	s_waitcnt lgkmcnt(1)
	v_mov_b32_e32 v52, v45
	v_mov_b32_e32 v53, v46
	v_mov_b32_e32 v45, v47
	s_waitcnt lgkmcnt(0)
	v_mov_b32_e32 v46, v49
	v_mov_b32_e32 v47, v50
	v_mov_b32_e32 v49, v51
	v_pk_add_f32 v[44:45], v[52:53], v[44:45]
	v_pk_add_f32 v[46:47], v[46:47], v[48:49]
	v_mov_b32_e32 v49, v44
	v_mov_b32_e32 v48, v46
	v_mov_b32_e32 v44, v47
	v_pk_add_f32 v[44:45], v[48:49], v[44:45]
	s_nop 0
	v_pk_fma_f32 v[44:45], v[44:45], s[34:35], v[16:17] op_sel_hi:[1,0,0]
	s_nop 0
	v_mul_f32_e32 v16, 0x4b800000, v45
	v_cmp_gt_f32_e32 vcc, s62, v45
	s_nop 1
	v_cndmask_b32_e32 v16, v45, v16, vcc
	v_rsq_f32_e32 v45, v16
	v_lshl_add_u64 v[16:17], s[14:15], 0, v[18:19]
	v_lshl_add_u64 v[16:17], v[16:17], 0, s[44:45]
	v_lshl_add_u64 v[46:47], v[16:17], 0, v[136:137]
	v_mul_f32_e32 v16, 0x45800000, v45
	v_cndmask_b32_e32 v16, v45, v16, vcc
	v_mul_f32_e32 v48, 0x3d800000, v16
	v_pk_mul_f32 v[16:17], v[32:33], v[48:49] op_sel_hi:[1,0]
	v_pk_mul_f32 v[18:19], v[28:29], v[48:49] op_sel_hi:[1,0]
	v_pk_mul_f32 v[28:29], v[34:35], v[48:49] op_sel_hi:[1,0]
	v_pk_mul_f32 v[30:31], v[30:31], v[48:49] op_sel_hi:[1,0]
	v_pk_mul_f32 v[24:25], v[24:25], v[48:49] op_sel_hi:[1,0]
	v_pk_mul_f32 v[22:23], v[22:23], v[48:49] op_sel_hi:[1,0]
	v_pk_mul_f32 v[26:27], v[26:27], v[48:49] op_sel_hi:[1,0]
	v_pk_mul_f32 v[20:21], v[20:21], v[48:49] op_sel_hi:[1,0]
	v_cmp_gt_f32_e32 vcc, s62, v44
	v_pk_mul_f32 v[18:19], v[18:19], v[214:215]
	v_pk_mul_f32 v[16:17], v[16:17], v[212:213]
	v_pk_mul_f32 v[30:31], v[30:31], v[218:219]
	v_pk_mul_f32 v[28:29], v[28:29], v[216:217]
	v_cvt_pk_bf16_f32 v16, v16, v17
	v_cvt_pk_bf16_f32 v17, v18, v19
	v_cvt_pk_bf16_f32 v18, v28, v29
	v_cvt_pk_bf16_f32 v19, v30, v31
	global_store_dwordx4 v[46:47], v[16:19], off nt
	s_nop 1
	s_nop 0
	v_pk_mul_f32 v[18:19], v[22:23], v[222:223]
	v_pk_mul_f32 v[16:17], v[24:25], v[220:221]
	v_pk_mul_f32 v[20:21], v[20:21], v[226:227]
	v_pk_mul_f32 v[22:23], v[26:27], v[224:225]
	v_cvt_pk_bf16_f32 v16, v16, v17
	v_cvt_pk_bf16_f32 v17, v18, v19
	v_cvt_pk_bf16_f32 v18, v22, v23
	v_cvt_pk_bf16_f32 v19, v20, v21
	global_store_dwordx4 v[46:47], v[16:19], off offset:256 nt
	s_nop 1
	s_nop 0
	v_mul_f32_e32 v26, 0x4b800000, v44
	v_cndmask_b32_e32 v26, v44, v26, vcc
	v_rsq_f32_e32 v26, v26
	v_lshlrev_b64 v[24:25], 11, v[148:149]
	v_lshl_add_u64 v[24:25], s[14:15], 0, v[24:25]
	v_lshl_add_u64 v[24:25], v[24:25], 0, s[44:45]
	v_mul_f32_e32 v27, 0x45800000, v26
	v_cndmask_b32_e32 v26, v26, v27, vcc
	v_mul_f32_e32 v26, 0x3d800000, v26
	v_pk_mul_f32 v[14:15], v[14:15], v[26:27] op_sel_hi:[1,0]
	v_pk_mul_f32 v[12:13], v[12:13], v[26:27] op_sel_hi:[1,0]
	v_pk_mul_f32 v[8:9], v[8:9], v[26:27] op_sel_hi:[1,0]
	v_pk_mul_f32 v[10:11], v[10:11], v[26:27] op_sel_hi:[1,0]
	v_lshl_add_u64 v[24:25], v[24:25], 0, v[136:137]
	v_pk_mul_f32 v[4:5], v[4:5], v[26:27] op_sel_hi:[1,0]
	v_pk_mul_f32 v[6:7], v[6:7], v[26:27] op_sel_hi:[1,0]
	v_pk_mul_f32 v[0:1], v[0:1], v[26:27] op_sel_hi:[1,0]
	v_pk_mul_f32 v[2:3], v[2:3], v[26:27] op_sel_hi:[1,0]
	s_mov_b64 s[44:45], -1
	s_and_b64 vcc, s[42:43], exec
	v_pk_mul_f32 v[12:13], v[12:13], v[214:215]
	v_pk_mul_f32 v[14:15], v[14:15], v[212:213]
	v_pk_mul_f32 v[16:17], v[10:11], v[218:219]
	v_pk_mul_f32 v[10:11], v[8:9], v[216:217]
	v_cvt_pk_bf16_f32 v8, v14, v15
	v_cvt_pk_bf16_f32 v9, v12, v13
	v_cvt_pk_bf16_f32 v10, v10, v11
	v_cvt_pk_bf16_f32 v11, v16, v17
	global_store_dwordx4 v[24:25], v[8:11], off nt
	s_nop 1
	s_nop 0
	v_pk_mul_f32 v[6:7], v[6:7], v[222:223]
	v_pk_mul_f32 v[4:5], v[4:5], v[220:221]
	v_pk_mul_f32 v[8:9], v[2:3], v[226:227]
	v_pk_mul_f32 v[2:3], v[0:1], v[224:225]
	v_cvt_pk_bf16_f32 v0, v4, v5
	v_cvt_pk_bf16_f32 v1, v6, v7
	v_cvt_pk_bf16_f32 v2, v2, v3
	v_cvt_pk_bf16_f32 v3, v8, v9
	global_store_dwordx4 v[24:25], v[0:3], off offset:256
	s_nop 1
	s_cbranch_vccz .LBB0_771
	s_andn2_b64 vcc, exec, s[20:21]
	s_cbranch_vccnz .LBB0_770
	s_barrier
	s_branch .LBB0_770
